# cache-policy hint: nt on the read-once residual-row loads of the P8 norm loop
# baseline (speedup 1.0000x reference)
.LBB0_1142:
	v_mul_hi_i32 v2, v50, s71
	v_lshrrev_b32_e32 v3, 31, v2
	v_ashrrev_i32_e32 v2, 9, v2
	v_add_u32_e32 v2, v2, v3
	v_mad_i32_i24 v3, v2, s73, v50
	s_movk_i32 s10, 0xff
	v_cmp_lt_i32_e32 vcc, s10, v3
	v_readlane_b32 s10, v255, 14
	v_readlane_b32 s11, v255, 15
	s_or_b64 s[12:13], s[10:11], vcc
	s_and_saveexec_b64 s[10:11], s[12:13]
	s_cbranch_execz .LBB0_1141
	v_ashrrev_i32_e32 v51, 31, v50
	v_lshlrev_b64 v[82:83], 11, v[50:51]
	v_lshl_add_u64 v[4:5], v[52:53], 0, v[82:83]
	global_load_dwordx4 v[46:49], v[4:5], off nt
	global_load_dwordx4 v[42:45], v[4:5], off offset:1024 nt
	v_add_u32_e32 v4, 1, v50
	v_ashrrev_i32_e32 v5, 31, v4
	v_cndmask_b32_e32 v2, 32, v2, vcc
	v_readlane_b32 s12, v255, 9
	v_lshlrev_b64 v[80:81], 11, v[4:5]
	v_lshl_add_u64 v[4:5], v[52:53], 0, v[80:81]
	v_add_u32_e32 v2, s12, v2
	v_mul_i32_i24_e32 v2, 6, v2
	global_load_dwordx4 v[38:41], v[4:5], off nt
	global_load_dwordx4 v[34:37], v[4:5], off offset:1024 nt
	v_add_u32_e32 v4, 2, v50
	v_ashrrev_i32_e32 v3, 31, v2
	v_ashrrev_i32_e32 v5, 31, v4
	v_lshlrev_b64 v[2:3], 12, v[2:3]
	v_lshlrev_b64 v[78:79], 11, v[4:5]
	v_lshl_add_u64 v[2:3], s[66:67], 0, v[2:3]
	v_lshl_add_u64 v[4:5], v[52:53], 0, v[78:79]
	s_mov_b64 s[12:13], 0x4000
	global_load_dwordx4 v[30:33], v[4:5], off nt
	global_load_dwordx4 v[26:29], v[4:5], off offset:1024 nt
	v_add_u32_e32 v4, 3, v50
	v_lshl_add_u64 v[74:75], v[2:3], 0, s[12:13]
	v_lshl_add_u64 v[2:3], v[2:3], 0, v[0:1]
	s_mov_b64 s[12:13], 0x3000
	v_ashrrev_i32_e32 v5, 31, v4
	v_lshl_add_u64 v[76:77], v[2:3], 0, s[12:13]
	s_movk_i32 s12, 0x3000
	v_lshlrev_b64 v[60:61], 11, v[4:5]
	v_add_co_u32_e32 v2, vcc, s12, v2
	v_lshl_add_u64 v[4:5], v[52:53], 0, v[60:61]
	s_nop 0
	v_addc_co_u32_e32 v3, vcc, 0, v3, vcc
	v_lshl_add_u64 v[66:67], v[74:75], 0, v[0:1]
	global_load_dwordx4 v[22:25], v[4:5], off nt
	global_load_dwordx4 v[18:21], v[4:5], off offset:1024 nt
	global_load_dwordx4 v[10:13], v[56:57], off offset:16
	global_load_dwordx4 v[14:17], v[56:57], off
	global_load_dwordx4 v[6:9], v[2:3], off
	s_nop 0
	global_load_dwordx4 v[2:5], v[76:77], off offset:16
	global_load_dwordx4 v[62:65], v[66:67], off offset:16
	s_nop 0
	global_load_dwordx4 v[66:69], v[66:67], off
	v_mov_b32_e32 v59, v1
	v_lshl_add_u64 v[74:75], v[74:75], 0, v[58:59]
	v_cmp_lt_i32_e32 vcc, v228, v225
	v_lshl_add_u64 v[82:83], v[54:55], 0, v[82:83]
	v_lshl_add_u64 v[80:81], v[54:55], 0, v[80:81]
	v_cndmask_b32_e32 v51, v224, v228, vcc
	v_lshlrev_b32_e32 v97, 2, v51
	v_cmp_lt_i32_e32 vcc, v227, v225
	s_waitcnt vmcnt(0)
	v_pk_add_f32 v[68:69], v[68:69], 1.0 op_sel_hi:[1,0]
	v_pk_add_f32 v[70:71], v[66:67], 1.0 op_sel_hi:[1,0]
	v_pk_mul_f32 v[66:67], v[16:17], v[68:69]
	v_pk_mul_f32 v[68:69], v[14:15], v[70:71]
	v_pk_add_f32 v[14:15], v[64:65], 1.0 op_sel_hi:[1,0]
	v_pk_add_f32 v[16:17], v[62:63], 1.0 op_sel_hi:[1,0]
	v_pk_mul_f32 v[62:63], v[12:13], v[14:15]
	v_pk_mul_f32 v[64:65], v[10:11], v[16:17]
	global_load_dwordx4 v[84:87], v[56:57], off offset:2064
	global_load_dwordx4 v[70:73], v[56:57], off offset:2048
	global_load_dwordx4 v[10:13], v[76:77], off offset:2064
	global_load_dwordx4 v[14:17], v[76:77], off offset:2048
	global_load_dwordx4 v[88:91], v[74:75], off offset:16
	s_nop 0
	global_load_dwordx4 v[74:77], v[74:75], off
	v_cndmask_b32_e32 v51, v224, v227, vcc
	v_lshlrev_b32_e32 v96, 2, v51
	v_cmp_lt_i32_e32 vcc, v226, v225
	s_waitcnt vmcnt(0)
	v_pk_add_f32 v[76:77], v[76:77], 1.0 op_sel_hi:[1,0]
	v_pk_add_f32 v[92:93], v[74:75], 1.0 op_sel_hi:[1,0]
	v_pk_mul_f32 v[74:75], v[72:73], v[76:77]
	v_pk_mul_f32 v[76:77], v[70:71], v[92:93]
	v_pk_add_f32 v[70:71], v[90:91], 1.0 op_sel_hi:[1,0]
	v_pk_add_f32 v[72:73], v[88:89], 1.0 op_sel_hi:[1,0]
	v_pk_mul_f32 v[70:71], v[86:87], v[70:71]
	v_and_b32_e32 v87, 0xffff0000, v48
	v_and_b32_e32 v86, 0xffff0000, v46
	v_lshlrev_b32_e32 v89, 16, v48
	v_lshlrev_b32_e32 v88, 16, v46
	v_lshlrev_b32_e32 v90, 16, v47
	v_and_b32_e32 v92, 0xffff0000, v47
	v_pk_mul_f32 v[46:47], v[86:87], v[86:87]
	v_lshlrev_b32_e32 v91, 16, v49
	v_pk_fma_f32 v[46:47], v[88:89], v[88:89], v[46:47]
	v_pk_mul_f32 v[72:73], v[84:85], v[72:73]
	v_and_b32_e32 v93, 0xffff0000, v49
	v_pk_fma_f32 v[46:47], v[90:91], v[90:91], v[46:47]
	v_and_b32_e32 v85, 0xffff0000, v42
	v_and_b32_e32 v84, 0xffff0000, v44
	v_pk_fma_f32 v[98:99], v[92:93], v[92:93], v[46:47]
	v_lshlrev_b32_e32 v47, 16, v42
	v_lshlrev_b32_e32 v46, 16, v44
	v_lshlrev_b32_e32 v48, 16, v45
	v_and_b32_e32 v42, 0xffff0000, v45
	v_pk_mul_f32 v[44:45], v[84:85], v[84:85]
	v_lshlrev_b32_e32 v49, 16, v43
	v_pk_fma_f32 v[44:45], v[46:47], v[46:47], v[44:45]
	v_and_b32_e32 v43, 0xffff0000, v43
	v_pk_fma_f32 v[44:45], v[48:49], v[48:49], v[44:45]
	v_add_f32_e32 v98, v98, v99
	v_pk_fma_f32 v[44:45], v[42:43], v[42:43], v[44:45]
	v_cndmask_b32_e32 v51, v224, v226, vcc
	v_add_f32_e32 v45, v98, v45
	v_add_f32_e32 v44, v44, v45
	ds_bpermute_b32 v45, v97, v44
	v_lshlrev_b32_e32 v95, 2, v51
	v_xor_b32_e32 v51, 4, v224
	v_cmp_lt_i32_e32 vcc, v51, v225
	v_mov_b32_e32 v98, v88
	s_waitcnt lgkmcnt(0)
	v_add_f32_e32 v44, v44, v45
	ds_bpermute_b32 v45, v96, v44
	v_cndmask_b32_e32 v51, v224, v51, vcc
	v_lshlrev_b32_e32 v94, 2, v51
	v_xor_b32_e32 v51, 2, v224
	v_cmp_lt_i32_e32 vcc, v51, v225
	s_waitcnt lgkmcnt(0)
	v_add_f32_e32 v44, v44, v45
	ds_bpermute_b32 v45, v95, v44
	v_cndmask_b32_e32 v51, v224, v51, vcc
	v_lshlrev_b32_e32 v59, 2, v51
	v_xor_b32_e32 v51, 1, v224
	v_cmp_lt_i32_e32 vcc, v51, v225
	s_waitcnt lgkmcnt(0)
	v_add_f32_e32 v44, v44, v45
	ds_bpermute_b32 v45, v94, v44
	v_cndmask_b32_e32 v51, v224, v51, vcc
	v_lshlrev_b32_e32 v51, 2, v51
	v_mov_b32_e32 v99, v86
	v_mov_b32_e32 v101, v92
	s_waitcnt lgkmcnt(0)
	v_add_f32_e32 v44, v44, v45
	ds_bpermute_b32 v45, v59, v44
	v_mov_b32_e32 v86, v89
	v_mov_b32_e32 v92, v91
	v_mov_b32_e32 v100, v90
	s_waitcnt lgkmcnt(0)
	v_add_f32_e32 v44, v44, v45
	ds_bpermute_b32 v45, v51, v44
	s_waitcnt lgkmcnt(0)
	v_add_f32_e32 v44, v44, v45
	v_fmamk_f32 v44, v44, 0x3a800000, v220
	v_cmp_gt_f32_e32 vcc, s93, v44
	v_mul_f32_e32 v45, 0x4b800000, v44
	s_nop 0
	v_cndmask_b32_e32 v44, v44, v45, vcc
	v_rsq_f32_e32 v44, v44
	s_nop 0
	v_mul_f32_e32 v45, 0x45800000, v44
	v_cndmask_b32_e32 v44, v44, v45, vcc
	v_pk_mul_f32 v[98:99], v[44:45], v[98:99] op_sel_hi:[0,1]
	v_pk_mul_f32 v[86:87], v[44:45], v[86:87] op_sel_hi:[0,1]
	v_pk_mul_f32 v[88:89], v[44:45], v[92:93] op_sel_hi:[0,1]
	v_pk_mul_f32 v[100:101], v[44:45], v[100:101] op_sel_hi:[0,1]
	v_pk_fma_f32 v[98:99], v[68:69], v[98:99], v[6:7]
	v_pk_fma_f32 v[90:91], v[62:63], v[88:89], v[4:5]
	v_pk_fma_f32 v[88:89], v[64:65], v[86:87], v[2:3]
	v_cvt_pk_bf16_f32 v86, v98, v99
	v_pk_fma_f32 v[100:101], v[66:67], v[100:101], v[8:9]
	s_nop 0
	v_cvt_pk_bf16_f32 v87, v100, v101
	v_cvt_pk_bf16_f32 v88, v88, v89
	v_cvt_pk_bf16_f32 v89, v90, v91
	global_store_dwordx4 v[82:83], v[86:89], off
	s_nop 1
	v_mov_b32_e32 v86, v47
	v_mov_b32_e32 v47, v84
	v_mov_b32_e32 v87, v85
	v_mov_b32_e32 v88, v49
	v_mov_b32_e32 v89, v43
	v_pk_mul_f32 v[46:47], v[44:45], v[46:47] op_sel_hi:[0,1]
	v_mov_b32_e32 v49, v42
	v_pk_mul_f32 v[86:87], v[44:45], v[86:87] op_sel_hi:[0,1]
	v_pk_mul_f32 v[88:89], v[44:45], v[88:89] op_sel_hi:[0,1]
	v_pk_mul_f32 v[42:43], v[44:45], v[48:49] op_sel_hi:[0,1]
	v_pk_fma_f32 v[44:45], v[72:73], v[46:47], v[10:11]
	v_pk_fma_f32 v[88:89], v[74:75], v[88:89], v[16:17]
	v_pk_fma_f32 v[86:87], v[76:77], v[86:87], v[14:15]
	v_pk_fma_f32 v[48:49], v[70:71], v[42:43], v[12:13]
	v_cvt_pk_bf16_f32 v42, v86, v87
	v_cvt_pk_bf16_f32 v43, v88, v89
	v_cvt_pk_bf16_f32 v44, v44, v45
	v_lshlrev_b32_e32 v46, 16, v39
	v_cvt_pk_bf16_f32 v45, v48, v49
	global_store_dwordx4 v[82:83], v[42:45], off offset:1024
	v_and_b32_e32 v83, 0xffff0000, v34
	v_and_b32_e32 v82, 0xffff0000, v36
	v_and_b32_e32 v45, 0xffff0000, v40
	v_and_b32_e32 v44, 0xffff0000, v38
	v_lshlrev_b32_e32 v43, 16, v40
	v_lshlrev_b32_e32 v42, 16, v38
	v_and_b32_e32 v40, 0xffff0000, v39
	v_pk_mul_f32 v[38:39], v[44:45], v[44:45]
	v_lshlrev_b32_e32 v47, 16, v41
	v_pk_fma_f32 v[38:39], v[42:43], v[42:43], v[38:39]
	v_lshlrev_b32_e32 v49, 16, v34
	v_lshlrev_b32_e32 v48, 16, v36
	v_lshlrev_b32_e32 v85, 16, v35
	v_and_b32_e32 v87, 0xffff0000, v35
	v_pk_mul_f32 v[34:35], v[82:83], v[82:83]
	v_and_b32_e32 v41, 0xffff0000, v41
	v_pk_fma_f32 v[38:39], v[46:47], v[46:47], v[38:39]
	v_lshlrev_b32_e32 v84, 16, v37
	v_pk_fma_f32 v[34:35], v[48:49], v[48:49], v[34:35]
	v_pk_fma_f32 v[38:39], v[40:41], v[40:41], v[38:39]
	v_and_b32_e32 v86, 0xffff0000, v37
	v_pk_fma_f32 v[34:35], v[84:85], v[84:85], v[34:35]
	v_add_f32_e32 v36, v38, v39
	v_pk_fma_f32 v[34:35], v[86:87], v[86:87], v[34:35]
	v_mov_b32_e32 v37, v40
	v_add_f32_e32 v35, v36, v35
	v_add_f32_e32 v34, v34, v35
	ds_bpermute_b32 v35, v97, v34
	v_mov_b32_e32 v36, v46
	v_mov_b32_e32 v40, v47
	v_and_b32_e32 v47, 0xffff0000, v27
	v_and_b32_e32 v46, 0xffff0000, v29
	s_waitcnt lgkmcnt(0)
	v_add_f32_e32 v34, v34, v35
	ds_bpermute_b32 v35, v96, v34
	s_waitcnt lgkmcnt(0)
	v_add_f32_e32 v34, v34, v35
	ds_bpermute_b32 v35, v95, v34
	s_waitcnt lgkmcnt(0)
	v_add_f32_e32 v34, v34, v35
	ds_bpermute_b32 v35, v94, v34
	s_waitcnt lgkmcnt(0)
	v_add_f32_e32 v34, v34, v35
	ds_bpermute_b32 v35, v59, v34
	s_waitcnt lgkmcnt(0)
	v_add_f32_e32 v34, v34, v35
	ds_bpermute_b32 v35, v51, v34
	s_waitcnt lgkmcnt(0)
	v_add_f32_e32 v34, v34, v35
	v_fmamk_f32 v34, v34, 0x3a800000, v220
	v_cmp_gt_f32_e32 vcc, s93, v34
	v_mul_f32_e32 v35, 0x4b800000, v34
	s_nop 0
	v_cndmask_b32_e32 v34, v34, v35, vcc
	v_rsq_f32_e32 v34, v34
	s_nop 0
	v_mul_f32_e32 v35, 0x45800000, v34
	v_cndmask_b32_e32 v38, v34, v35, vcc
	v_mov_b32_e32 v34, v42
	v_mov_b32_e32 v35, v44
	v_pk_mul_f32 v[34:35], v[38:39], v[34:35] op_sel_hi:[0,1]
	v_pk_mul_f32 v[36:37], v[38:39], v[36:37] op_sel_hi:[0,1]
	v_mov_b32_e32 v44, v43
	v_pk_fma_f32 v[36:37], v[66:67], v[36:37], v[8:9]
	v_pk_fma_f32 v[34:35], v[68:69], v[34:35], v[6:7]
	v_pk_mul_f32 v[42:43], v[38:39], v[44:45] op_sel_hi:[0,1]
	v_pk_mul_f32 v[40:41], v[38:39], v[40:41] op_sel_hi:[0,1]
	v_pk_fma_f32 v[40:41], v[62:63], v[40:41], v[4:5]
	v_pk_fma_f32 v[42:43], v[64:65], v[42:43], v[2:3]
	v_cvt_pk_bf16_f32 v34, v34, v35
	v_cvt_pk_bf16_f32 v35, v36, v37
	v_lshlrev_b32_e32 v45, 16, v27
	v_cvt_pk_bf16_f32 v36, v42, v43
	v_cvt_pk_bf16_f32 v37, v40, v41
	global_store_dwordx4 v[80:81], v[34:37], off
	v_and_b32_e32 v43, 0xffff0000, v26
	v_and_b32_e32 v42, 0xffff0000, v28
	v_mov_b32_e32 v34, v49
	v_mov_b32_e32 v35, v83
	v_mov_b32_e32 v36, v85
	v_mov_b32_e32 v37, v87
	v_pk_mul_f32 v[34:35], v[38:39], v[34:35] op_sel_hi:[0,1]
	v_pk_mul_f32 v[36:37], v[38:39], v[36:37] op_sel_hi:[0,1]
	v_mov_b32_e32 v49, v82
	v_mov_b32_e32 v85, v86
	v_pk_fma_f32 v[36:37], v[74:75], v[36:37], v[16:17]
	v_pk_fma_f32 v[34:35], v[76:77], v[34:35], v[14:15]
	v_pk_mul_f32 v[40:41], v[38:39], v[48:49] op_sel_hi:[0,1]
	v_pk_mul_f32 v[38:39], v[38:39], v[84:85] op_sel_hi:[0,1]
	v_pk_fma_f32 v[38:39], v[70:71], v[38:39], v[12:13]
	v_pk_fma_f32 v[40:41], v[72:73], v[40:41], v[10:11]
	v_cvt_pk_bf16_f32 v34, v34, v35
	v_cvt_pk_bf16_f32 v35, v36, v37
	v_lshlrev_b32_e32 v44, 16, v29
	v_cvt_pk_bf16_f32 v36, v40, v41
	v_cvt_pk_bf16_f32 v37, v38, v39
	global_store_dwordx4 v[80:81], v[34:37], off offset:1024
	v_lshlrev_b32_e32 v38, 16, v31
	v_lshlrev_b32_e32 v39, 16, v33
	v_and_b32_e32 v37, 0xffff0000, v32
	v_and_b32_e32 v36, 0xffff0000, v30
	v_lshlrev_b32_e32 v35, 16, v32
	v_lshlrev_b32_e32 v34, 16, v30
	v_and_b32_e32 v32, 0xffff0000, v31
	v_pk_mul_f32 v[30:31], v[36:37], v[36:37]
	v_lshlrev_b32_e32 v41, 16, v26
	v_pk_fma_f32 v[30:31], v[34:35], v[34:35], v[30:31]
	v_lshlrev_b32_e32 v40, 16, v28
	v_pk_mul_f32 v[26:27], v[42:43], v[42:43]
	v_and_b32_e32 v33, 0xffff0000, v33
	v_pk_fma_f32 v[30:31], v[38:39], v[38:39], v[30:31]
	v_pk_fma_f32 v[26:27], v[40:41], v[40:41], v[26:27]
	v_pk_fma_f32 v[30:31], v[32:33], v[32:33], v[30:31]
	v_pk_fma_f32 v[26:27], v[44:45], v[44:45], v[26:27]
	v_add_f32_e32 v28, v30, v31
	v_pk_fma_f32 v[26:27], v[46:47], v[46:47], v[26:27]
	v_mov_b32_e32 v29, v32
	v_add_f32_e32 v27, v28, v27
	v_add_f32_e32 v26, v26, v27
	ds_bpermute_b32 v27, v97, v26
	v_mov_b32_e32 v28, v38
	v_mov_b32_e32 v32, v39
	v_lshl_add_u64 v[48:49], v[54:55], 0, v[78:79]
	s_waitcnt lgkmcnt(0)
	v_add_f32_e32 v26, v26, v27
	ds_bpermute_b32 v27, v96, v26
	s_waitcnt lgkmcnt(0)
	v_add_f32_e32 v26, v26, v27
	ds_bpermute_b32 v27, v95, v26
	s_waitcnt lgkmcnt(0)
	v_add_f32_e32 v26, v26, v27
	ds_bpermute_b32 v27, v94, v26
	s_waitcnt lgkmcnt(0)
	v_add_f32_e32 v26, v26, v27
	ds_bpermute_b32 v27, v59, v26
	s_waitcnt lgkmcnt(0)
	v_add_f32_e32 v26, v26, v27
	ds_bpermute_b32 v27, v51, v26
	s_waitcnt lgkmcnt(0)
	v_add_f32_e32 v26, v26, v27
	v_fmamk_f32 v26, v26, 0x3a800000, v220
	v_cmp_gt_f32_e32 vcc, s93, v26
	v_mul_f32_e32 v27, 0x4b800000, v26
	s_nop 0
	v_cndmask_b32_e32 v26, v26, v27, vcc
	v_rsq_f32_e32 v26, v26
	s_nop 0
	v_mul_f32_e32 v27, 0x45800000, v26
	v_cndmask_b32_e32 v30, v26, v27, vcc
	v_mov_b32_e32 v26, v34
	v_mov_b32_e32 v27, v36
	v_pk_mul_f32 v[26:27], v[30:31], v[26:27] op_sel_hi:[0,1]
	v_pk_mul_f32 v[28:29], v[30:31], v[28:29] op_sel_hi:[0,1]
	v_mov_b32_e32 v36, v35
	v_pk_fma_f32 v[28:29], v[66:67], v[28:29], v[8:9]
	v_pk_fma_f32 v[26:27], v[68:69], v[26:27], v[6:7]
	v_pk_mul_f32 v[34:35], v[30:31], v[36:37] op_sel_hi:[0,1]
	v_pk_mul_f32 v[32:33], v[30:31], v[32:33] op_sel_hi:[0,1]
	v_pk_fma_f32 v[32:33], v[62:63], v[32:33], v[4:5]
	v_pk_fma_f32 v[34:35], v[64:65], v[34:35], v[2:3]
	v_cvt_pk_bf16_f32 v26, v26, v27
	v_cvt_pk_bf16_f32 v27, v28, v29
	v_lshlrev_b32_e32 v36, 16, v21
	v_cvt_pk_bf16_f32 v28, v34, v35
	v_cvt_pk_bf16_f32 v29, v32, v33
	global_store_dwordx4 v[48:49], v[26:29], off
	v_and_b32_e32 v35, 0xffff0000, v18
	v_and_b32_e32 v34, 0xffff0000, v20
	v_mov_b32_e32 v26, v41
	v_mov_b32_e32 v27, v43
	v_mov_b32_e32 v28, v45
	v_mov_b32_e32 v29, v47
	v_pk_mul_f32 v[26:27], v[30:31], v[26:27] op_sel_hi:[0,1]
	v_pk_mul_f32 v[28:29], v[30:31], v[28:29] op_sel_hi:[0,1]
	v_mov_b32_e32 v41, v42
	v_mov_b32_e32 v45, v46
	v_pk_fma_f32 v[28:29], v[74:75], v[28:29], v[16:17]
	v_pk_fma_f32 v[26:27], v[76:77], v[26:27], v[14:15]
	v_pk_mul_f32 v[32:33], v[30:31], v[40:41] op_sel_hi:[0,1]
	v_pk_mul_f32 v[30:31], v[30:31], v[44:45] op_sel_hi:[0,1]
	v_pk_fma_f32 v[30:31], v[70:71], v[30:31], v[12:13]
	v_pk_fma_f32 v[32:33], v[72:73], v[32:33], v[10:11]
	v_cvt_pk_bf16_f32 v26, v26, v27
	v_cvt_pk_bf16_f32 v27, v28, v29
	v_lshlrev_b32_e32 v37, 16, v19
	v_cvt_pk_bf16_f32 v28, v32, v33
	v_cvt_pk_bf16_f32 v29, v30, v31
	global_store_dwordx4 v[48:49], v[26:29], off offset:1024
	v_lshlrev_b32_e32 v30, 16, v23
	v_lshlrev_b32_e32 v31, 16, v25
	v_and_b32_e32 v29, 0xffff0000, v24
	v_and_b32_e32 v28, 0xffff0000, v22
	v_lshlrev_b32_e32 v27, 16, v24
	v_lshlrev_b32_e32 v26, 16, v22
	v_and_b32_e32 v24, 0xffff0000, v23
	v_pk_mul_f32 v[22:23], v[28:29], v[28:29]
	v_lshlrev_b32_e32 v33, 16, v18
	v_pk_fma_f32 v[22:23], v[26:27], v[26:27], v[22:23]
	v_lshlrev_b32_e32 v32, 16, v20
	v_and_b32_e32 v18, 0xffff0000, v21
	v_pk_mul_f32 v[20:21], v[34:35], v[34:35]
	v_and_b32_e32 v25, 0xffff0000, v25
	v_pk_fma_f32 v[22:23], v[30:31], v[30:31], v[22:23]
	v_pk_fma_f32 v[20:21], v[32:33], v[32:33], v[20:21]
	v_pk_fma_f32 v[22:23], v[24:25], v[24:25], v[22:23]
	v_and_b32_e32 v19, 0xffff0000, v19
	v_pk_fma_f32 v[20:21], v[36:37], v[36:37], v[20:21]
	v_add_f32_e32 v22, v22, v23
	v_pk_fma_f32 v[20:21], v[18:19], v[18:19], v[20:21]
	v_mov_b32_e32 v39, v28
	v_add_f32_e32 v21, v22, v21
	v_add_f32_e32 v20, v20, v21
	ds_bpermute_b32 v21, v97, v20
	v_mov_b32_e32 v41, v24
	v_mov_b32_e32 v28, v27
	v_mov_b32_e32 v24, v31
	v_mov_b32_e32 v38, v26
	s_waitcnt lgkmcnt(0)
	v_add_f32_e32 v20, v20, v21
	ds_bpermute_b32 v21, v96, v20
	v_mov_b32_e32 v40, v30
	v_lshl_add_u64 v[22:23], v[54:55], 0, v[60:61]
	s_waitcnt lgkmcnt(0)
	v_add_f32_e32 v20, v20, v21
	ds_bpermute_b32 v21, v95, v20
	s_waitcnt lgkmcnt(0)
	v_add_f32_e32 v20, v20, v21
	ds_bpermute_b32 v21, v94, v20
	s_waitcnt lgkmcnt(0)
	v_add_f32_e32 v20, v20, v21
	ds_bpermute_b32 v21, v59, v20
	s_waitcnt lgkmcnt(0)
	v_add_f32_e32 v20, v20, v21
	ds_bpermute_b32 v21, v51, v20
	s_waitcnt lgkmcnt(0)
	v_add_f32_e32 v20, v20, v21
	v_fmamk_f32 v20, v20, 0x3a800000, v220
	v_cmp_gt_f32_e32 vcc, s93, v20
	v_mul_f32_e32 v21, 0x4b800000, v20
	s_nop 0
	v_cndmask_b32_e32 v20, v20, v21, vcc
	v_rsq_f32_e32 v20, v20
	s_nop 0
	v_mul_f32_e32 v21, 0x45800000, v20
	v_cndmask_b32_e32 v20, v20, v21, vcc
	v_pk_mul_f32 v[26:27], v[20:21], v[28:29] op_sel_hi:[0,1]
	v_pk_mul_f32 v[24:25], v[20:21], v[24:25] op_sel_hi:[0,1]
	v_pk_mul_f32 v[38:39], v[20:21], v[38:39] op_sel_hi:[0,1]
	v_pk_mul_f32 v[40:41], v[20:21], v[40:41] op_sel_hi:[0,1]
	v_pk_fma_f32 v[24:25], v[62:63], v[24:25], v[4:5]
	v_pk_fma_f32 v[4:5], v[64:65], v[26:27], v[2:3]
	v_pk_fma_f32 v[8:9], v[66:67], v[40:41], v[8:9]
	v_pk_fma_f32 v[6:7], v[68:69], v[38:39], v[6:7]
	s_nop 0
	v_cvt_pk_bf16_f32 v2, v6, v7
	v_cvt_pk_bf16_f32 v3, v8, v9
	v_cvt_pk_bf16_f32 v4, v4, v5
	v_cvt_pk_bf16_f32 v5, v24, v25
	global_store_dwordx4 v[22:23], v[2:5], off
	s_nop 1
	v_mov_b32_e32 v2, v33
	v_mov_b32_e32 v3, v35
	v_mov_b32_e32 v4, v37
	v_mov_b32_e32 v5, v19
	v_pk_mul_f32 v[2:3], v[20:21], v[2:3] op_sel_hi:[0,1]
	v_pk_mul_f32 v[4:5], v[20:21], v[4:5] op_sel_hi:[0,1]
	v_mov_b32_e32 v33, v34
	v_mov_b32_e32 v37, v18
	v_pk_fma_f32 v[4:5], v[74:75], v[4:5], v[16:17]
	v_pk_fma_f32 v[2:3], v[76:77], v[2:3], v[14:15]
	v_pk_mul_f32 v[6:7], v[20:21], v[32:33] op_sel_hi:[0,1]
	v_pk_mul_f32 v[8:9], v[20:21], v[36:37] op_sel_hi:[0,1]
	v_pk_fma_f32 v[8:9], v[70:71], v[8:9], v[12:13]
	v_pk_fma_f32 v[6:7], v[72:73], v[6:7], v[10:11]
	v_cvt_pk_bf16_f32 v2, v2, v3
	v_cvt_pk_bf16_f32 v3, v4, v5
	s_nop 0
	v_cvt_pk_bf16_f32 v4, v6, v7
	v_cvt_pk_bf16_f32 v5, v8, v9
	global_store_dwordx4 v[22:23], v[2:5], off offset:1024
	s_branch .LBB0_1141
